# P5 C-state scan rewritten with 16-byte loads/stores (256 threads/WG, 8 elements each, saddr addressing) on top of best
# baseline (speedup 1.0000x reference)
.LBB0_879:
	s_or_b64 exec, exec, s[10:11]
	v_mov_b32_e32 v66, v0
	s_waitcnt lgkmcnt(0)
	s_barrier
	s_mov_b32 s3, 0x20000
	v_add_u32_e32 v67, s84, v66
	v_cmp_gt_u32_e32 vcc, 0x100, v66
	s_and_saveexec_b64 s[10:11], vcc
	s_cbranch_execz .LBB0_882
	s_load_dwordx2 s[0:1], s[96:97], 0xe8
	s_lshr_b32 s4, s2, 5
	s_and_b32 s5, s4, 3
	s_lshr_b32 s6, s4, 2
	s_and_b32 s7, s2, 31
	s_lshl_b32 s7, s7, 12
	v_lshlrev_b32_e32 v2, 4, v66
	v_add_u32_e32 v2, s7, v2
	v_mov_b32_e32 v3, 0
	s_lshl_b32 s8, s4, 22
	s_lshl_b32 s9, s6, 17
	s_lshl_b32 s16, s5, 2
	s_add_i32 s9, s9, s16
	s_add_i32 s9, s9, 0x2399ff0
	s_waitcnt lgkmcnt(0)
	s_add_u32 s12, s0, 0x4e00000
	s_addc_u32 s13, s1, 0
	s_add_u32 s12, s12, s8
	s_addc_u32 s13, s13, 0
	s_mov_b64 s[20:21], s[12:13]
	s_add_u32 s14, s0, s9
	s_addc_u32 s15, s1, 0
	s_nop 1
	global_load_dword v140, v3, s[14:15]
	s_add_u32 s14, s14, 0x1000
	s_addc_u32 s15, s15, 0
	s_nop 0
	global_load_dword v141, v3, s[14:15]
	s_add_u32 s14, s14, 0x1000
	s_addc_u32 s15, s15, 0
	s_nop 0
	global_load_dword v142, v3, s[14:15]
	s_add_u32 s14, s14, 0x1000
	s_addc_u32 s15, s15, 0
	s_nop 0
	global_load_dword v143, v3, s[14:15]
	s_add_u32 s14, s14, 0x1000
	s_addc_u32 s15, s15, 0
	s_nop 0
	global_load_dword v144, v3, s[14:15]
	s_add_u32 s14, s14, 0x1000
	s_addc_u32 s15, s15, 0
	s_nop 0
	global_load_dword v145, v3, s[14:15]
	s_add_u32 s14, s14, 0x1000
	s_addc_u32 s15, s15, 0
	s_nop 0
	global_load_dword v146, v3, s[14:15]
	s_add_u32 s14, s14, 0x1000
	s_addc_u32 s15, s15, 0
	s_nop 0
	global_load_dword v147, v3, s[14:15]
	s_add_u32 s14, s14, 0x1000
	s_addc_u32 s15, s15, 0
	s_nop 0
	global_load_dword v148, v3, s[14:15]
	s_add_u32 s14, s14, 0x1000
	s_addc_u32 s15, s15, 0
	s_nop 0
	global_load_dword v149, v3, s[14:15]
	s_add_u32 s14, s14, 0x1000
	s_addc_u32 s15, s15, 0
	s_nop 0
	global_load_dword v150, v3, s[14:15]
	s_add_u32 s14, s14, 0x1000
	s_addc_u32 s15, s15, 0
	s_nop 0
	global_load_dword v151, v3, s[14:15]
	s_add_u32 s14, s14, 0x1000
	s_addc_u32 s15, s15, 0
	s_nop 0
	global_load_dword v152, v3, s[14:15]
	s_add_u32 s14, s14, 0x1000
	s_addc_u32 s15, s15, 0
	s_nop 0
	global_load_dword v153, v3, s[14:15]
	s_add_u32 s14, s14, 0x1000
	s_addc_u32 s15, s15, 0
	s_nop 0
	global_load_dword v154, v3, s[14:15]
	s_add_u32 s14, s14, 0x1000
	s_addc_u32 s15, s15, 0
	s_nop 0
	global_load_dword v155, v3, s[14:15]
	s_add_u32 s14, s14, 0x1000
	s_addc_u32 s15, s15, 0
	s_nop 0
	global_load_dword v156, v3, s[14:15]
	s_add_u32 s14, s14, 0x1000
	s_addc_u32 s15, s15, 0
	s_nop 0
	global_load_dword v157, v3, s[14:15]
	s_add_u32 s14, s14, 0x1000
	s_addc_u32 s15, s15, 0
	s_nop 0
	global_load_dword v158, v3, s[14:15]
	s_add_u32 s14, s14, 0x1000
	s_addc_u32 s15, s15, 0
	s_nop 0
	global_load_dword v159, v3, s[14:15]
	s_add_u32 s14, s14, 0x1000
	s_addc_u32 s15, s15, 0
	s_nop 0
	global_load_dword v160, v3, s[14:15]
	s_add_u32 s14, s14, 0x1000
	s_addc_u32 s15, s15, 0
	s_nop 0
	global_load_dword v161, v3, s[14:15]
	s_add_u32 s14, s14, 0x1000
	s_addc_u32 s15, s15, 0
	s_nop 0
	global_load_dword v162, v3, s[14:15]
	s_add_u32 s14, s14, 0x1000
	s_addc_u32 s15, s15, 0
	s_nop 0
	global_load_dword v163, v3, s[14:15]
	s_add_u32 s14, s14, 0x1000
	s_addc_u32 s15, s15, 0
	s_nop 0
	global_load_dword v164, v3, s[14:15]
	s_add_u32 s14, s14, 0x1000
	s_addc_u32 s15, s15, 0
	s_nop 0
	global_load_dword v165, v3, s[14:15]
	s_add_u32 s14, s14, 0x1000
	s_addc_u32 s15, s15, 0
	s_nop 0
	global_load_dword v166, v3, s[14:15]
	s_add_u32 s14, s14, 0x1000
	s_addc_u32 s15, s15, 0
	s_nop 0
	global_load_dword v167, v3, s[14:15]
	s_add_u32 s14, s14, 0x1000
	s_addc_u32 s15, s15, 0
	s_nop 0
	global_load_dword v168, v3, s[14:15]
	s_add_u32 s14, s14, 0x1000
	s_addc_u32 s15, s15, 0
	s_nop 0
	global_load_dword v169, v3, s[14:15]
	s_add_u32 s14, s14, 0x1000
	s_addc_u32 s15, s15, 0
	s_nop 0
	global_load_dword v170, v3, s[14:15]
	s_add_u32 s14, s14, 0x1000
	s_addc_u32 s15, s15, 0
	s_nop 0
	global_load_dword v171, v3, s[14:15]
	global_load_dwordx4 v[8:11], v2, s[12:13]
	s_add_u32 s12, s12, 0x20000
	s_addc_u32 s13, s13, 0
	s_nop 0
	global_load_dwordx4 v[12:15], v2, s[12:13]
	s_add_u32 s12, s12, 0x20000
	s_addc_u32 s13, s13, 0
	s_nop 0
	global_load_dwordx4 v[16:19], v2, s[12:13]
	s_add_u32 s12, s12, 0x20000
	s_addc_u32 s13, s13, 0
	s_nop 0
	global_load_dwordx4 v[20:23], v2, s[12:13]
	s_add_u32 s12, s12, 0x20000
	s_addc_u32 s13, s13, 0
	s_nop 0
	global_load_dwordx4 v[24:27], v2, s[12:13]
	s_add_u32 s12, s12, 0x20000
	s_addc_u32 s13, s13, 0
	s_nop 0
	global_load_dwordx4 v[28:31], v2, s[12:13]
	s_add_u32 s12, s12, 0x20000
	s_addc_u32 s13, s13, 0
	s_nop 0
	global_load_dwordx4 v[32:35], v2, s[12:13]
	s_add_u32 s12, s12, 0x20000
	s_addc_u32 s13, s13, 0
	s_nop 0
	global_load_dwordx4 v[36:39], v2, s[12:13]
	s_add_u32 s12, s12, 0x20000
	s_addc_u32 s13, s13, 0
	s_nop 0
	global_load_dwordx4 v[40:43], v2, s[12:13]
	s_add_u32 s12, s12, 0x20000
	s_addc_u32 s13, s13, 0
	s_nop 0
	global_load_dwordx4 v[44:47], v2, s[12:13]
	s_add_u32 s12, s12, 0x20000
	s_addc_u32 s13, s13, 0
	s_nop 0
	global_load_dwordx4 v[48:51], v2, s[12:13]
	s_add_u32 s12, s12, 0x20000
	s_addc_u32 s13, s13, 0
	s_nop 0
	global_load_dwordx4 v[52:55], v2, s[12:13]
	s_add_u32 s12, s12, 0x20000
	s_addc_u32 s13, s13, 0
	s_nop 0
	global_load_dwordx4 v[56:59], v2, s[12:13]
	s_add_u32 s12, s12, 0x20000
	s_addc_u32 s13, s13, 0
	s_nop 0
	global_load_dwordx4 v[60:63], v2, s[12:13]
	s_add_u32 s12, s12, 0x20000
	s_addc_u32 s13, s13, 0
	s_nop 0
	global_load_dwordx4 v[68:71], v2, s[12:13]
	s_add_u32 s12, s12, 0x20000
	s_addc_u32 s13, s13, 0
	s_nop 0
	global_load_dwordx4 v[72:75], v2, s[12:13]
	s_add_u32 s12, s12, 0x20000
	s_addc_u32 s13, s13, 0
	s_nop 0
	global_load_dwordx4 v[76:79], v2, s[12:13]
	s_add_u32 s12, s12, 0x20000
	s_addc_u32 s13, s13, 0
	s_nop 0
	global_load_dwordx4 v[80:83], v2, s[12:13]
	s_add_u32 s12, s12, 0x20000
	s_addc_u32 s13, s13, 0
	s_nop 0
	global_load_dwordx4 v[84:87], v2, s[12:13]
	s_add_u32 s12, s12, 0x20000
	s_addc_u32 s13, s13, 0
	s_nop 0
	global_load_dwordx4 v[88:91], v2, s[12:13]
	s_add_u32 s12, s12, 0x20000
	s_addc_u32 s13, s13, 0
	s_nop 0
	global_load_dwordx4 v[92:95], v2, s[12:13]
	s_add_u32 s12, s12, 0x20000
	s_addc_u32 s13, s13, 0
	s_nop 0
	global_load_dwordx4 v[96:99], v2, s[12:13]
	s_add_u32 s12, s12, 0x20000
	s_addc_u32 s13, s13, 0
	s_nop 0
	global_load_dwordx4 v[100:103], v2, s[12:13]
	s_add_u32 s12, s12, 0x20000
	s_addc_u32 s13, s13, 0
	s_nop 0
	global_load_dwordx4 v[104:107], v2, s[12:13]
	s_add_u32 s12, s12, 0x20000
	s_addc_u32 s13, s13, 0
	s_nop 0
	global_load_dwordx4 v[108:111], v2, s[12:13]
	s_add_u32 s12, s12, 0x20000
	s_addc_u32 s13, s13, 0
	s_nop 0
	global_load_dwordx4 v[112:115], v2, s[12:13]
	s_add_u32 s12, s12, 0x20000
	s_addc_u32 s13, s13, 0
	s_nop 0
	global_load_dwordx4 v[116:119], v2, s[12:13]
	s_add_u32 s12, s12, 0x20000
	s_addc_u32 s13, s13, 0
	s_nop 0
	global_load_dwordx4 v[120:123], v2, s[12:13]
	s_add_u32 s12, s12, 0x20000
	s_addc_u32 s13, s13, 0
	s_nop 0
	global_load_dwordx4 v[124:127], v2, s[12:13]
	s_add_u32 s12, s12, 0x20000
	s_addc_u32 s13, s13, 0
	s_nop 0
	global_load_dwordx4 v[128:131], v2, s[12:13]
	s_add_u32 s12, s12, 0x20000
	s_addc_u32 s13, s13, 0
	s_nop 0
	global_load_dwordx4 v[132:135], v2, s[12:13]
	s_add_u32 s12, s12, 0x20000
	s_addc_u32 s13, s13, 0
	s_nop 0
	global_load_dwordx4 v[136:139], v2, s[12:13]
	v_mov_b32_e32 v172, 0
	v_mov_b32_e32 v173, 0
	v_mov_b32_e32 v174, 0
	v_mov_b32_e32 v175, 0
	v_mov_b32_e32 v176, 0
	v_mov_b32_e32 v177, 0
	v_mov_b32_e32 v178, 0
	v_mov_b32_e32 v179, 0
	s_waitcnt vmcnt(31)
	v_sub_f32_e32 v182, v3, v140
	v_mul_f32_e32 v182, 0x3fb8aa3b, v182
	v_exp_f32_e32 v180, v182
	v_cvt_pk_bf16_f32 v184, v172, v173
	v_cvt_pk_bf16_f32 v185, v174, v175
	v_cvt_pk_bf16_f32 v186, v176, v177
	v_cvt_pk_bf16_f32 v187, v178, v179
	v_lshlrev_b32_e32 v192, 16, v8
	v_and_b32_e32 v193, 0xffff0000, v8
	v_lshlrev_b32_e32 v194, 16, v9
	v_and_b32_e32 v195, 0xffff0000, v9
	v_lshlrev_b32_e32 v196, 16, v10
	v_and_b32_e32 v197, 0xffff0000, v10
	v_lshlrev_b32_e32 v198, 16, v11
	v_and_b32_e32 v199, 0xffff0000, v11
	global_store_dwordx4 v2, v[184:187], s[20:21]
	s_add_u32 s20, s20, 0x20000
	s_addc_u32 s21, s21, 0
	v_fmac_f32_e32 v192, v172, v180
	v_fmac_f32_e32 v193, v173, v180
	v_fmac_f32_e32 v194, v174, v180
	v_fmac_f32_e32 v195, v175, v180
	v_fmac_f32_e32 v196, v176, v180
	v_fmac_f32_e32 v197, v177, v180
	v_fmac_f32_e32 v198, v178, v180
	v_fmac_f32_e32 v199, v179, v180
	s_waitcnt vmcnt(31)
	v_sub_f32_e32 v182, v140, v141
	v_mul_f32_e32 v182, 0x3fb8aa3b, v182
	v_exp_f32_e32 v180, v182
	v_cvt_pk_bf16_f32 v188, v192, v193
	v_cvt_pk_bf16_f32 v189, v194, v195
	v_cvt_pk_bf16_f32 v190, v196, v197
	v_cvt_pk_bf16_f32 v191, v198, v199
	v_lshlrev_b32_e32 v172, 16, v12
	v_and_b32_e32 v173, 0xffff0000, v12
	v_lshlrev_b32_e32 v174, 16, v13
	v_and_b32_e32 v175, 0xffff0000, v13
	v_lshlrev_b32_e32 v176, 16, v14
	v_and_b32_e32 v177, 0xffff0000, v14
	v_lshlrev_b32_e32 v178, 16, v15
	v_and_b32_e32 v179, 0xffff0000, v15
	global_store_dwordx4 v2, v[188:191], s[20:21]
	s_add_u32 s20, s20, 0x20000
	s_addc_u32 s21, s21, 0
	v_fmac_f32_e32 v172, v192, v180
	v_fmac_f32_e32 v173, v193, v180
	v_fmac_f32_e32 v174, v194, v180
	v_fmac_f32_e32 v175, v195, v180
	v_fmac_f32_e32 v176, v196, v180
	v_fmac_f32_e32 v177, v197, v180
	v_fmac_f32_e32 v178, v198, v180
	v_fmac_f32_e32 v179, v199, v180
	s_waitcnt vmcnt(31)
	v_sub_f32_e32 v182, v141, v142
	v_mul_f32_e32 v182, 0x3fb8aa3b, v182
	v_exp_f32_e32 v180, v182
	v_cvt_pk_bf16_f32 v184, v172, v173
	v_cvt_pk_bf16_f32 v185, v174, v175
	v_cvt_pk_bf16_f32 v186, v176, v177
	v_cvt_pk_bf16_f32 v187, v178, v179
	v_lshlrev_b32_e32 v192, 16, v16
	v_and_b32_e32 v193, 0xffff0000, v16
	v_lshlrev_b32_e32 v194, 16, v17
	v_and_b32_e32 v195, 0xffff0000, v17
	v_lshlrev_b32_e32 v196, 16, v18
	v_and_b32_e32 v197, 0xffff0000, v18
	v_lshlrev_b32_e32 v198, 16, v19
	v_and_b32_e32 v199, 0xffff0000, v19
	global_store_dwordx4 v2, v[184:187], s[20:21]
	s_add_u32 s20, s20, 0x20000
	s_addc_u32 s21, s21, 0
	v_fmac_f32_e32 v192, v172, v180
	v_fmac_f32_e32 v193, v173, v180
	v_fmac_f32_e32 v194, v174, v180
	v_fmac_f32_e32 v195, v175, v180
	v_fmac_f32_e32 v196, v176, v180
	v_fmac_f32_e32 v197, v177, v180
	v_fmac_f32_e32 v198, v178, v180
	v_fmac_f32_e32 v199, v179, v180
	s_waitcnt vmcnt(31)
	v_sub_f32_e32 v182, v142, v143
	v_mul_f32_e32 v182, 0x3fb8aa3b, v182
	v_exp_f32_e32 v180, v182
	v_cvt_pk_bf16_f32 v188, v192, v193
	v_cvt_pk_bf16_f32 v189, v194, v195
	v_cvt_pk_bf16_f32 v190, v196, v197
	v_cvt_pk_bf16_f32 v191, v198, v199
	v_lshlrev_b32_e32 v172, 16, v20
	v_and_b32_e32 v173, 0xffff0000, v20
	v_lshlrev_b32_e32 v174, 16, v21
	v_and_b32_e32 v175, 0xffff0000, v21
	v_lshlrev_b32_e32 v176, 16, v22
	v_and_b32_e32 v177, 0xffff0000, v22
	v_lshlrev_b32_e32 v178, 16, v23
	v_and_b32_e32 v179, 0xffff0000, v23
	global_store_dwordx4 v2, v[188:191], s[20:21]
	s_add_u32 s20, s20, 0x20000
	s_addc_u32 s21, s21, 0
	v_fmac_f32_e32 v172, v192, v180
	v_fmac_f32_e32 v173, v193, v180
	v_fmac_f32_e32 v174, v194, v180
	v_fmac_f32_e32 v175, v195, v180
	v_fmac_f32_e32 v176, v196, v180
	v_fmac_f32_e32 v177, v197, v180
	v_fmac_f32_e32 v178, v198, v180
	v_fmac_f32_e32 v179, v199, v180
	s_waitcnt vmcnt(31)
	v_sub_f32_e32 v182, v143, v144
	v_mul_f32_e32 v182, 0x3fb8aa3b, v182
	v_exp_f32_e32 v180, v182
	v_cvt_pk_bf16_f32 v184, v172, v173
	v_cvt_pk_bf16_f32 v185, v174, v175
	v_cvt_pk_bf16_f32 v186, v176, v177
	v_cvt_pk_bf16_f32 v187, v178, v179
	v_lshlrev_b32_e32 v192, 16, v24
	v_and_b32_e32 v193, 0xffff0000, v24
	v_lshlrev_b32_e32 v194, 16, v25
	v_and_b32_e32 v195, 0xffff0000, v25
	v_lshlrev_b32_e32 v196, 16, v26
	v_and_b32_e32 v197, 0xffff0000, v26
	v_lshlrev_b32_e32 v198, 16, v27
	v_and_b32_e32 v199, 0xffff0000, v27
	global_store_dwordx4 v2, v[184:187], s[20:21]
	s_add_u32 s20, s20, 0x20000
	s_addc_u32 s21, s21, 0
	v_fmac_f32_e32 v192, v172, v180
	v_fmac_f32_e32 v193, v173, v180
	v_fmac_f32_e32 v194, v174, v180
	v_fmac_f32_e32 v195, v175, v180
	v_fmac_f32_e32 v196, v176, v180
	v_fmac_f32_e32 v197, v177, v180
	v_fmac_f32_e32 v198, v178, v180
	v_fmac_f32_e32 v199, v179, v180
	s_waitcnt vmcnt(31)
	v_sub_f32_e32 v182, v144, v145
	v_mul_f32_e32 v182, 0x3fb8aa3b, v182
	v_exp_f32_e32 v180, v182
	v_cvt_pk_bf16_f32 v188, v192, v193
	v_cvt_pk_bf16_f32 v189, v194, v195
	v_cvt_pk_bf16_f32 v190, v196, v197
	v_cvt_pk_bf16_f32 v191, v198, v199
	v_lshlrev_b32_e32 v172, 16, v28
	v_and_b32_e32 v173, 0xffff0000, v28
	v_lshlrev_b32_e32 v174, 16, v29
	v_and_b32_e32 v175, 0xffff0000, v29
	v_lshlrev_b32_e32 v176, 16, v30
	v_and_b32_e32 v177, 0xffff0000, v30
	v_lshlrev_b32_e32 v178, 16, v31
	v_and_b32_e32 v179, 0xffff0000, v31
	global_store_dwordx4 v2, v[188:191], s[20:21]
	s_add_u32 s20, s20, 0x20000
	s_addc_u32 s21, s21, 0
	v_fmac_f32_e32 v172, v192, v180
	v_fmac_f32_e32 v173, v193, v180
	v_fmac_f32_e32 v174, v194, v180
	v_fmac_f32_e32 v175, v195, v180
	v_fmac_f32_e32 v176, v196, v180
	v_fmac_f32_e32 v177, v197, v180
	v_fmac_f32_e32 v178, v198, v180
	v_fmac_f32_e32 v179, v199, v180
	s_waitcnt vmcnt(31)
	v_sub_f32_e32 v182, v145, v146
	v_mul_f32_e32 v182, 0x3fb8aa3b, v182
	v_exp_f32_e32 v180, v182
	v_cvt_pk_bf16_f32 v184, v172, v173
	v_cvt_pk_bf16_f32 v185, v174, v175
	v_cvt_pk_bf16_f32 v186, v176, v177
	v_cvt_pk_bf16_f32 v187, v178, v179
	v_lshlrev_b32_e32 v192, 16, v32
	v_and_b32_e32 v193, 0xffff0000, v32
	v_lshlrev_b32_e32 v194, 16, v33
	v_and_b32_e32 v195, 0xffff0000, v33
	v_lshlrev_b32_e32 v196, 16, v34
	v_and_b32_e32 v197, 0xffff0000, v34
	v_lshlrev_b32_e32 v198, 16, v35
	v_and_b32_e32 v199, 0xffff0000, v35
	global_store_dwordx4 v2, v[184:187], s[20:21]
	s_add_u32 s20, s20, 0x20000
	s_addc_u32 s21, s21, 0
	v_fmac_f32_e32 v192, v172, v180
	v_fmac_f32_e32 v193, v173, v180
	v_fmac_f32_e32 v194, v174, v180
	v_fmac_f32_e32 v195, v175, v180
	v_fmac_f32_e32 v196, v176, v180
	v_fmac_f32_e32 v197, v177, v180
	v_fmac_f32_e32 v198, v178, v180
	v_fmac_f32_e32 v199, v179, v180
	s_waitcnt vmcnt(31)
	v_sub_f32_e32 v182, v146, v147
	v_mul_f32_e32 v182, 0x3fb8aa3b, v182
	v_exp_f32_e32 v180, v182
	v_cvt_pk_bf16_f32 v188, v192, v193
	v_cvt_pk_bf16_f32 v189, v194, v195
	v_cvt_pk_bf16_f32 v190, v196, v197
	v_cvt_pk_bf16_f32 v191, v198, v199
	v_lshlrev_b32_e32 v172, 16, v36
	v_and_b32_e32 v173, 0xffff0000, v36
	v_lshlrev_b32_e32 v174, 16, v37
	v_and_b32_e32 v175, 0xffff0000, v37
	v_lshlrev_b32_e32 v176, 16, v38
	v_and_b32_e32 v177, 0xffff0000, v38
	v_lshlrev_b32_e32 v178, 16, v39
	v_and_b32_e32 v179, 0xffff0000, v39
	global_store_dwordx4 v2, v[188:191], s[20:21]
	s_add_u32 s20, s20, 0x20000
	s_addc_u32 s21, s21, 0
	v_fmac_f32_e32 v172, v192, v180
	v_fmac_f32_e32 v173, v193, v180
	v_fmac_f32_e32 v174, v194, v180
	v_fmac_f32_e32 v175, v195, v180
	v_fmac_f32_e32 v176, v196, v180
	v_fmac_f32_e32 v177, v197, v180
	v_fmac_f32_e32 v178, v198, v180
	v_fmac_f32_e32 v179, v199, v180
	s_waitcnt vmcnt(31)
	v_sub_f32_e32 v182, v147, v148
	v_mul_f32_e32 v182, 0x3fb8aa3b, v182
	v_exp_f32_e32 v180, v182
	v_cvt_pk_bf16_f32 v184, v172, v173
	v_cvt_pk_bf16_f32 v185, v174, v175
	v_cvt_pk_bf16_f32 v186, v176, v177
	v_cvt_pk_bf16_f32 v187, v178, v179
	v_lshlrev_b32_e32 v192, 16, v40
	v_and_b32_e32 v193, 0xffff0000, v40
	v_lshlrev_b32_e32 v194, 16, v41
	v_and_b32_e32 v195, 0xffff0000, v41
	v_lshlrev_b32_e32 v196, 16, v42
	v_and_b32_e32 v197, 0xffff0000, v42
	v_lshlrev_b32_e32 v198, 16, v43
	v_and_b32_e32 v199, 0xffff0000, v43
	global_store_dwordx4 v2, v[184:187], s[20:21]
	s_add_u32 s20, s20, 0x20000
	s_addc_u32 s21, s21, 0
	v_fmac_f32_e32 v192, v172, v180
	v_fmac_f32_e32 v193, v173, v180
	v_fmac_f32_e32 v194, v174, v180
	v_fmac_f32_e32 v195, v175, v180
	v_fmac_f32_e32 v196, v176, v180
	v_fmac_f32_e32 v197, v177, v180
	v_fmac_f32_e32 v198, v178, v180
	v_fmac_f32_e32 v199, v179, v180
	s_waitcnt vmcnt(31)
	v_sub_f32_e32 v182, v148, v149
	v_mul_f32_e32 v182, 0x3fb8aa3b, v182
	v_exp_f32_e32 v180, v182
	v_cvt_pk_bf16_f32 v188, v192, v193
	v_cvt_pk_bf16_f32 v189, v194, v195
	v_cvt_pk_bf16_f32 v190, v196, v197
	v_cvt_pk_bf16_f32 v191, v198, v199
	v_lshlrev_b32_e32 v172, 16, v44
	v_and_b32_e32 v173, 0xffff0000, v44
	v_lshlrev_b32_e32 v174, 16, v45
	v_and_b32_e32 v175, 0xffff0000, v45
	v_lshlrev_b32_e32 v176, 16, v46
	v_and_b32_e32 v177, 0xffff0000, v46
	v_lshlrev_b32_e32 v178, 16, v47
	v_and_b32_e32 v179, 0xffff0000, v47
	global_store_dwordx4 v2, v[188:191], s[20:21]
	s_add_u32 s20, s20, 0x20000
	s_addc_u32 s21, s21, 0
	v_fmac_f32_e32 v172, v192, v180
	v_fmac_f32_e32 v173, v193, v180
	v_fmac_f32_e32 v174, v194, v180
	v_fmac_f32_e32 v175, v195, v180
	v_fmac_f32_e32 v176, v196, v180
	v_fmac_f32_e32 v177, v197, v180
	v_fmac_f32_e32 v178, v198, v180
	v_fmac_f32_e32 v179, v199, v180
	s_waitcnt vmcnt(31)
	v_sub_f32_e32 v182, v149, v150
	v_mul_f32_e32 v182, 0x3fb8aa3b, v182
	v_exp_f32_e32 v180, v182
	v_cvt_pk_bf16_f32 v184, v172, v173
	v_cvt_pk_bf16_f32 v185, v174, v175
	v_cvt_pk_bf16_f32 v186, v176, v177
	v_cvt_pk_bf16_f32 v187, v178, v179
	v_lshlrev_b32_e32 v192, 16, v48
	v_and_b32_e32 v193, 0xffff0000, v48
	v_lshlrev_b32_e32 v194, 16, v49
	v_and_b32_e32 v195, 0xffff0000, v49
	v_lshlrev_b32_e32 v196, 16, v50
	v_and_b32_e32 v197, 0xffff0000, v50
	v_lshlrev_b32_e32 v198, 16, v51
	v_and_b32_e32 v199, 0xffff0000, v51
	global_store_dwordx4 v2, v[184:187], s[20:21]
	s_add_u32 s20, s20, 0x20000
	s_addc_u32 s21, s21, 0
	v_fmac_f32_e32 v192, v172, v180
	v_fmac_f32_e32 v193, v173, v180
	v_fmac_f32_e32 v194, v174, v180
	v_fmac_f32_e32 v195, v175, v180
	v_fmac_f32_e32 v196, v176, v180
	v_fmac_f32_e32 v197, v177, v180
	v_fmac_f32_e32 v198, v178, v180
	v_fmac_f32_e32 v199, v179, v180
	s_waitcnt vmcnt(31)
	v_sub_f32_e32 v182, v150, v151
	v_mul_f32_e32 v182, 0x3fb8aa3b, v182
	v_exp_f32_e32 v180, v182
	v_cvt_pk_bf16_f32 v188, v192, v193
	v_cvt_pk_bf16_f32 v189, v194, v195
	v_cvt_pk_bf16_f32 v190, v196, v197
	v_cvt_pk_bf16_f32 v191, v198, v199
	v_lshlrev_b32_e32 v172, 16, v52
	v_and_b32_e32 v173, 0xffff0000, v52
	v_lshlrev_b32_e32 v174, 16, v53
	v_and_b32_e32 v175, 0xffff0000, v53
	v_lshlrev_b32_e32 v176, 16, v54
	v_and_b32_e32 v177, 0xffff0000, v54
	v_lshlrev_b32_e32 v178, 16, v55
	v_and_b32_e32 v179, 0xffff0000, v55
	global_store_dwordx4 v2, v[188:191], s[20:21]
	s_add_u32 s20, s20, 0x20000
	s_addc_u32 s21, s21, 0
	v_fmac_f32_e32 v172, v192, v180
	v_fmac_f32_e32 v173, v193, v180
	v_fmac_f32_e32 v174, v194, v180
	v_fmac_f32_e32 v175, v195, v180
	v_fmac_f32_e32 v176, v196, v180
	v_fmac_f32_e32 v177, v197, v180
	v_fmac_f32_e32 v178, v198, v180
	v_fmac_f32_e32 v179, v199, v180
	s_waitcnt vmcnt(31)
	v_sub_f32_e32 v182, v151, v152
	v_mul_f32_e32 v182, 0x3fb8aa3b, v182
	v_exp_f32_e32 v180, v182
	v_cvt_pk_bf16_f32 v184, v172, v173
	v_cvt_pk_bf16_f32 v185, v174, v175
	v_cvt_pk_bf16_f32 v186, v176, v177
	v_cvt_pk_bf16_f32 v187, v178, v179
	v_lshlrev_b32_e32 v192, 16, v56
	v_and_b32_e32 v193, 0xffff0000, v56
	v_lshlrev_b32_e32 v194, 16, v57
	v_and_b32_e32 v195, 0xffff0000, v57
	v_lshlrev_b32_e32 v196, 16, v58
	v_and_b32_e32 v197, 0xffff0000, v58
	v_lshlrev_b32_e32 v198, 16, v59
	v_and_b32_e32 v199, 0xffff0000, v59
	global_store_dwordx4 v2, v[184:187], s[20:21]
	s_add_u32 s20, s20, 0x20000
	s_addc_u32 s21, s21, 0
	v_fmac_f32_e32 v192, v172, v180
	v_fmac_f32_e32 v193, v173, v180
	v_fmac_f32_e32 v194, v174, v180
	v_fmac_f32_e32 v195, v175, v180
	v_fmac_f32_e32 v196, v176, v180
	v_fmac_f32_e32 v197, v177, v180
	v_fmac_f32_e32 v198, v178, v180
	v_fmac_f32_e32 v199, v179, v180
	s_waitcnt vmcnt(31)
	v_sub_f32_e32 v182, v152, v153
	v_mul_f32_e32 v182, 0x3fb8aa3b, v182
	v_exp_f32_e32 v180, v182
	v_cvt_pk_bf16_f32 v188, v192, v193
	v_cvt_pk_bf16_f32 v189, v194, v195
	v_cvt_pk_bf16_f32 v190, v196, v197
	v_cvt_pk_bf16_f32 v191, v198, v199
	v_lshlrev_b32_e32 v172, 16, v60
	v_and_b32_e32 v173, 0xffff0000, v60
	v_lshlrev_b32_e32 v174, 16, v61
	v_and_b32_e32 v175, 0xffff0000, v61
	v_lshlrev_b32_e32 v176, 16, v62
	v_and_b32_e32 v177, 0xffff0000, v62
	v_lshlrev_b32_e32 v178, 16, v63
	v_and_b32_e32 v179, 0xffff0000, v63
	global_store_dwordx4 v2, v[188:191], s[20:21]
	s_add_u32 s20, s20, 0x20000
	s_addc_u32 s21, s21, 0
	v_fmac_f32_e32 v172, v192, v180
	v_fmac_f32_e32 v173, v193, v180
	v_fmac_f32_e32 v174, v194, v180
	v_fmac_f32_e32 v175, v195, v180
	v_fmac_f32_e32 v176, v196, v180
	v_fmac_f32_e32 v177, v197, v180
	v_fmac_f32_e32 v178, v198, v180
	v_fmac_f32_e32 v179, v199, v180
	s_waitcnt vmcnt(31)
	v_sub_f32_e32 v182, v153, v154
	v_mul_f32_e32 v182, 0x3fb8aa3b, v182
	v_exp_f32_e32 v180, v182
	v_cvt_pk_bf16_f32 v184, v172, v173
	v_cvt_pk_bf16_f32 v185, v174, v175
	v_cvt_pk_bf16_f32 v186, v176, v177
	v_cvt_pk_bf16_f32 v187, v178, v179
	v_lshlrev_b32_e32 v192, 16, v68
	v_and_b32_e32 v193, 0xffff0000, v68
	v_lshlrev_b32_e32 v194, 16, v69
	v_and_b32_e32 v195, 0xffff0000, v69
	v_lshlrev_b32_e32 v196, 16, v70
	v_and_b32_e32 v197, 0xffff0000, v70
	v_lshlrev_b32_e32 v198, 16, v71
	v_and_b32_e32 v199, 0xffff0000, v71
	global_store_dwordx4 v2, v[184:187], s[20:21]
	s_add_u32 s20, s20, 0x20000
	s_addc_u32 s21, s21, 0
	v_fmac_f32_e32 v192, v172, v180
	v_fmac_f32_e32 v193, v173, v180
	v_fmac_f32_e32 v194, v174, v180
	v_fmac_f32_e32 v195, v175, v180
	v_fmac_f32_e32 v196, v176, v180
	v_fmac_f32_e32 v197, v177, v180
	v_fmac_f32_e32 v198, v178, v180
	v_fmac_f32_e32 v199, v179, v180
	s_waitcnt vmcnt(31)
	v_sub_f32_e32 v182, v154, v155
	v_mul_f32_e32 v182, 0x3fb8aa3b, v182
	v_exp_f32_e32 v180, v182
	v_cvt_pk_bf16_f32 v188, v192, v193
	v_cvt_pk_bf16_f32 v189, v194, v195
	v_cvt_pk_bf16_f32 v190, v196, v197
	v_cvt_pk_bf16_f32 v191, v198, v199
	v_lshlrev_b32_e32 v172, 16, v72
	v_and_b32_e32 v173, 0xffff0000, v72
	v_lshlrev_b32_e32 v174, 16, v73
	v_and_b32_e32 v175, 0xffff0000, v73
	v_lshlrev_b32_e32 v176, 16, v74
	v_and_b32_e32 v177, 0xffff0000, v74
	v_lshlrev_b32_e32 v178, 16, v75
	v_and_b32_e32 v179, 0xffff0000, v75
	global_store_dwordx4 v2, v[188:191], s[20:21]
	s_add_u32 s20, s20, 0x20000
	s_addc_u32 s21, s21, 0
	v_fmac_f32_e32 v172, v192, v180
	v_fmac_f32_e32 v173, v193, v180
	v_fmac_f32_e32 v174, v194, v180
	v_fmac_f32_e32 v175, v195, v180
	v_fmac_f32_e32 v176, v196, v180
	v_fmac_f32_e32 v177, v197, v180
	v_fmac_f32_e32 v178, v198, v180
	v_fmac_f32_e32 v179, v199, v180
	s_waitcnt vmcnt(31)
	v_sub_f32_e32 v182, v155, v156
	v_mul_f32_e32 v182, 0x3fb8aa3b, v182
	v_exp_f32_e32 v180, v182
	v_cvt_pk_bf16_f32 v184, v172, v173
	v_cvt_pk_bf16_f32 v185, v174, v175
	v_cvt_pk_bf16_f32 v186, v176, v177
	v_cvt_pk_bf16_f32 v187, v178, v179
	v_lshlrev_b32_e32 v192, 16, v76
	v_and_b32_e32 v193, 0xffff0000, v76
	v_lshlrev_b32_e32 v194, 16, v77
	v_and_b32_e32 v195, 0xffff0000, v77
	v_lshlrev_b32_e32 v196, 16, v78
	v_and_b32_e32 v197, 0xffff0000, v78
	v_lshlrev_b32_e32 v198, 16, v79
	v_and_b32_e32 v199, 0xffff0000, v79
	global_store_dwordx4 v2, v[184:187], s[20:21]
	s_add_u32 s20, s20, 0x20000
	s_addc_u32 s21, s21, 0
	v_fmac_f32_e32 v192, v172, v180
	v_fmac_f32_e32 v193, v173, v180
	v_fmac_f32_e32 v194, v174, v180
	v_fmac_f32_e32 v195, v175, v180
	v_fmac_f32_e32 v196, v176, v180
	v_fmac_f32_e32 v197, v177, v180
	v_fmac_f32_e32 v198, v178, v180
	v_fmac_f32_e32 v199, v179, v180
	s_waitcnt vmcnt(31)
	v_sub_f32_e32 v182, v156, v157
	v_mul_f32_e32 v182, 0x3fb8aa3b, v182
	v_exp_f32_e32 v180, v182
	v_cvt_pk_bf16_f32 v188, v192, v193
	v_cvt_pk_bf16_f32 v189, v194, v195
	v_cvt_pk_bf16_f32 v190, v196, v197
	v_cvt_pk_bf16_f32 v191, v198, v199
	v_lshlrev_b32_e32 v172, 16, v80
	v_and_b32_e32 v173, 0xffff0000, v80
	v_lshlrev_b32_e32 v174, 16, v81
	v_and_b32_e32 v175, 0xffff0000, v81
	v_lshlrev_b32_e32 v176, 16, v82
	v_and_b32_e32 v177, 0xffff0000, v82
	v_lshlrev_b32_e32 v178, 16, v83
	v_and_b32_e32 v179, 0xffff0000, v83
	global_store_dwordx4 v2, v[188:191], s[20:21]
	s_add_u32 s20, s20, 0x20000
	s_addc_u32 s21, s21, 0
	v_fmac_f32_e32 v172, v192, v180
	v_fmac_f32_e32 v173, v193, v180
	v_fmac_f32_e32 v174, v194, v180
	v_fmac_f32_e32 v175, v195, v180
	v_fmac_f32_e32 v176, v196, v180
	v_fmac_f32_e32 v177, v197, v180
	v_fmac_f32_e32 v178, v198, v180
	v_fmac_f32_e32 v179, v199, v180
	s_waitcnt vmcnt(31)
	v_sub_f32_e32 v182, v157, v158
	v_mul_f32_e32 v182, 0x3fb8aa3b, v182
	v_exp_f32_e32 v180, v182
	v_cvt_pk_bf16_f32 v184, v172, v173
	v_cvt_pk_bf16_f32 v185, v174, v175
	v_cvt_pk_bf16_f32 v186, v176, v177
	v_cvt_pk_bf16_f32 v187, v178, v179
	v_lshlrev_b32_e32 v192, 16, v84
	v_and_b32_e32 v193, 0xffff0000, v84
	v_lshlrev_b32_e32 v194, 16, v85
	v_and_b32_e32 v195, 0xffff0000, v85
	v_lshlrev_b32_e32 v196, 16, v86
	v_and_b32_e32 v197, 0xffff0000, v86
	v_lshlrev_b32_e32 v198, 16, v87
	v_and_b32_e32 v199, 0xffff0000, v87
	global_store_dwordx4 v2, v[184:187], s[20:21]
	s_add_u32 s20, s20, 0x20000
	s_addc_u32 s21, s21, 0
	v_fmac_f32_e32 v192, v172, v180
	v_fmac_f32_e32 v193, v173, v180
	v_fmac_f32_e32 v194, v174, v180
	v_fmac_f32_e32 v195, v175, v180
	v_fmac_f32_e32 v196, v176, v180
	v_fmac_f32_e32 v197, v177, v180
	v_fmac_f32_e32 v198, v178, v180
	v_fmac_f32_e32 v199, v179, v180
	s_waitcnt vmcnt(31)
	v_sub_f32_e32 v182, v158, v159
	v_mul_f32_e32 v182, 0x3fb8aa3b, v182
	v_exp_f32_e32 v180, v182
	v_cvt_pk_bf16_f32 v188, v192, v193
	v_cvt_pk_bf16_f32 v189, v194, v195
	v_cvt_pk_bf16_f32 v190, v196, v197
	v_cvt_pk_bf16_f32 v191, v198, v199
	v_lshlrev_b32_e32 v172, 16, v88
	v_and_b32_e32 v173, 0xffff0000, v88
	v_lshlrev_b32_e32 v174, 16, v89
	v_and_b32_e32 v175, 0xffff0000, v89
	v_lshlrev_b32_e32 v176, 16, v90
	v_and_b32_e32 v177, 0xffff0000, v90
	v_lshlrev_b32_e32 v178, 16, v91
	v_and_b32_e32 v179, 0xffff0000, v91
	global_store_dwordx4 v2, v[188:191], s[20:21]
	s_add_u32 s20, s20, 0x20000
	s_addc_u32 s21, s21, 0
	v_fmac_f32_e32 v172, v192, v180
	v_fmac_f32_e32 v173, v193, v180
	v_fmac_f32_e32 v174, v194, v180
	v_fmac_f32_e32 v175, v195, v180
	v_fmac_f32_e32 v176, v196, v180
	v_fmac_f32_e32 v177, v197, v180
	v_fmac_f32_e32 v178, v198, v180
	v_fmac_f32_e32 v179, v199, v180
	s_waitcnt vmcnt(31)
	v_sub_f32_e32 v182, v159, v160
	v_mul_f32_e32 v182, 0x3fb8aa3b, v182
	v_exp_f32_e32 v180, v182
	v_cvt_pk_bf16_f32 v184, v172, v173
	v_cvt_pk_bf16_f32 v185, v174, v175
	v_cvt_pk_bf16_f32 v186, v176, v177
	v_cvt_pk_bf16_f32 v187, v178, v179
	v_lshlrev_b32_e32 v192, 16, v92
	v_and_b32_e32 v193, 0xffff0000, v92
	v_lshlrev_b32_e32 v194, 16, v93
	v_and_b32_e32 v195, 0xffff0000, v93
	v_lshlrev_b32_e32 v196, 16, v94
	v_and_b32_e32 v197, 0xffff0000, v94
	v_lshlrev_b32_e32 v198, 16, v95
	v_and_b32_e32 v199, 0xffff0000, v95
	global_store_dwordx4 v2, v[184:187], s[20:21]
	s_add_u32 s20, s20, 0x20000
	s_addc_u32 s21, s21, 0
	v_fmac_f32_e32 v192, v172, v180
	v_fmac_f32_e32 v193, v173, v180
	v_fmac_f32_e32 v194, v174, v180
	v_fmac_f32_e32 v195, v175, v180
	v_fmac_f32_e32 v196, v176, v180
	v_fmac_f32_e32 v197, v177, v180
	v_fmac_f32_e32 v198, v178, v180
	v_fmac_f32_e32 v199, v179, v180
	s_waitcnt vmcnt(31)
	v_sub_f32_e32 v182, v160, v161
	v_mul_f32_e32 v182, 0x3fb8aa3b, v182
	v_exp_f32_e32 v180, v182
	v_cvt_pk_bf16_f32 v188, v192, v193
	v_cvt_pk_bf16_f32 v189, v194, v195
	v_cvt_pk_bf16_f32 v190, v196, v197
	v_cvt_pk_bf16_f32 v191, v198, v199
	v_lshlrev_b32_e32 v172, 16, v96
	v_and_b32_e32 v173, 0xffff0000, v96
	v_lshlrev_b32_e32 v174, 16, v97
	v_and_b32_e32 v175, 0xffff0000, v97
	v_lshlrev_b32_e32 v176, 16, v98
	v_and_b32_e32 v177, 0xffff0000, v98
	v_lshlrev_b32_e32 v178, 16, v99
	v_and_b32_e32 v179, 0xffff0000, v99
	global_store_dwordx4 v2, v[188:191], s[20:21]
	s_add_u32 s20, s20, 0x20000
	s_addc_u32 s21, s21, 0
	v_fmac_f32_e32 v172, v192, v180
	v_fmac_f32_e32 v173, v193, v180
	v_fmac_f32_e32 v174, v194, v180
	v_fmac_f32_e32 v175, v195, v180
	v_fmac_f32_e32 v176, v196, v180
	v_fmac_f32_e32 v177, v197, v180
	v_fmac_f32_e32 v178, v198, v180
	v_fmac_f32_e32 v179, v199, v180
	s_waitcnt vmcnt(31)
	v_sub_f32_e32 v182, v161, v162
	v_mul_f32_e32 v182, 0x3fb8aa3b, v182
	v_exp_f32_e32 v180, v182
	v_cvt_pk_bf16_f32 v184, v172, v173
	v_cvt_pk_bf16_f32 v185, v174, v175
	v_cvt_pk_bf16_f32 v186, v176, v177
	v_cvt_pk_bf16_f32 v187, v178, v179
	v_lshlrev_b32_e32 v192, 16, v100
	v_and_b32_e32 v193, 0xffff0000, v100
	v_lshlrev_b32_e32 v194, 16, v101
	v_and_b32_e32 v195, 0xffff0000, v101
	v_lshlrev_b32_e32 v196, 16, v102
	v_and_b32_e32 v197, 0xffff0000, v102
	v_lshlrev_b32_e32 v198, 16, v103
	v_and_b32_e32 v199, 0xffff0000, v103
	global_store_dwordx4 v2, v[184:187], s[20:21]
	s_add_u32 s20, s20, 0x20000
	s_addc_u32 s21, s21, 0
	v_fmac_f32_e32 v192, v172, v180
	v_fmac_f32_e32 v193, v173, v180
	v_fmac_f32_e32 v194, v174, v180
	v_fmac_f32_e32 v195, v175, v180
	v_fmac_f32_e32 v196, v176, v180
	v_fmac_f32_e32 v197, v177, v180
	v_fmac_f32_e32 v198, v178, v180
	v_fmac_f32_e32 v199, v179, v180
	s_waitcnt vmcnt(31)
	v_sub_f32_e32 v182, v162, v163
	v_mul_f32_e32 v182, 0x3fb8aa3b, v182
	v_exp_f32_e32 v180, v182
	v_cvt_pk_bf16_f32 v188, v192, v193
	v_cvt_pk_bf16_f32 v189, v194, v195
	v_cvt_pk_bf16_f32 v190, v196, v197
	v_cvt_pk_bf16_f32 v191, v198, v199
	v_lshlrev_b32_e32 v172, 16, v104
	v_and_b32_e32 v173, 0xffff0000, v104
	v_lshlrev_b32_e32 v174, 16, v105
	v_and_b32_e32 v175, 0xffff0000, v105
	v_lshlrev_b32_e32 v176, 16, v106
	v_and_b32_e32 v177, 0xffff0000, v106
	v_lshlrev_b32_e32 v178, 16, v107
	v_and_b32_e32 v179, 0xffff0000, v107
	global_store_dwordx4 v2, v[188:191], s[20:21]
	s_add_u32 s20, s20, 0x20000
	s_addc_u32 s21, s21, 0
	v_fmac_f32_e32 v172, v192, v180
	v_fmac_f32_e32 v173, v193, v180
	v_fmac_f32_e32 v174, v194, v180
	v_fmac_f32_e32 v175, v195, v180
	v_fmac_f32_e32 v176, v196, v180
	v_fmac_f32_e32 v177, v197, v180
	v_fmac_f32_e32 v178, v198, v180
	v_fmac_f32_e32 v179, v199, v180
	s_waitcnt vmcnt(31)
	v_sub_f32_e32 v182, v163, v164
	v_mul_f32_e32 v182, 0x3fb8aa3b, v182
	v_exp_f32_e32 v180, v182
	v_cvt_pk_bf16_f32 v184, v172, v173
	v_cvt_pk_bf16_f32 v185, v174, v175
	v_cvt_pk_bf16_f32 v186, v176, v177
	v_cvt_pk_bf16_f32 v187, v178, v179
	v_lshlrev_b32_e32 v192, 16, v108
	v_and_b32_e32 v193, 0xffff0000, v108
	v_lshlrev_b32_e32 v194, 16, v109
	v_and_b32_e32 v195, 0xffff0000, v109
	v_lshlrev_b32_e32 v196, 16, v110
	v_and_b32_e32 v197, 0xffff0000, v110
	v_lshlrev_b32_e32 v198, 16, v111
	v_and_b32_e32 v199, 0xffff0000, v111
	global_store_dwordx4 v2, v[184:187], s[20:21]
	s_add_u32 s20, s20, 0x20000
	s_addc_u32 s21, s21, 0
	v_fmac_f32_e32 v192, v172, v180
	v_fmac_f32_e32 v193, v173, v180
	v_fmac_f32_e32 v194, v174, v180
	v_fmac_f32_e32 v195, v175, v180
	v_fmac_f32_e32 v196, v176, v180
	v_fmac_f32_e32 v197, v177, v180
	v_fmac_f32_e32 v198, v178, v180
	v_fmac_f32_e32 v199, v179, v180
	s_waitcnt vmcnt(31)
	v_sub_f32_e32 v182, v164, v165
	v_mul_f32_e32 v182, 0x3fb8aa3b, v182
	v_exp_f32_e32 v180, v182
	v_cvt_pk_bf16_f32 v188, v192, v193
	v_cvt_pk_bf16_f32 v189, v194, v195
	v_cvt_pk_bf16_f32 v190, v196, v197
	v_cvt_pk_bf16_f32 v191, v198, v199
	v_lshlrev_b32_e32 v172, 16, v112
	v_and_b32_e32 v173, 0xffff0000, v112
	v_lshlrev_b32_e32 v174, 16, v113
	v_and_b32_e32 v175, 0xffff0000, v113
	v_lshlrev_b32_e32 v176, 16, v114
	v_and_b32_e32 v177, 0xffff0000, v114
	v_lshlrev_b32_e32 v178, 16, v115
	v_and_b32_e32 v179, 0xffff0000, v115
	global_store_dwordx4 v2, v[188:191], s[20:21]
	s_add_u32 s20, s20, 0x20000
	s_addc_u32 s21, s21, 0
	v_fmac_f32_e32 v172, v192, v180
	v_fmac_f32_e32 v173, v193, v180
	v_fmac_f32_e32 v174, v194, v180
	v_fmac_f32_e32 v175, v195, v180
	v_fmac_f32_e32 v176, v196, v180
	v_fmac_f32_e32 v177, v197, v180
	v_fmac_f32_e32 v178, v198, v180
	v_fmac_f32_e32 v179, v199, v180
	s_waitcnt vmcnt(31)
	v_sub_f32_e32 v182, v165, v166
	v_mul_f32_e32 v182, 0x3fb8aa3b, v182
	v_exp_f32_e32 v180, v182
	v_cvt_pk_bf16_f32 v184, v172, v173
	v_cvt_pk_bf16_f32 v185, v174, v175
	v_cvt_pk_bf16_f32 v186, v176, v177
	v_cvt_pk_bf16_f32 v187, v178, v179
	v_lshlrev_b32_e32 v192, 16, v116
	v_and_b32_e32 v193, 0xffff0000, v116
	v_lshlrev_b32_e32 v194, 16, v117
	v_and_b32_e32 v195, 0xffff0000, v117
	v_lshlrev_b32_e32 v196, 16, v118
	v_and_b32_e32 v197, 0xffff0000, v118
	v_lshlrev_b32_e32 v198, 16, v119
	v_and_b32_e32 v199, 0xffff0000, v119
	global_store_dwordx4 v2, v[184:187], s[20:21]
	s_add_u32 s20, s20, 0x20000
	s_addc_u32 s21, s21, 0
	v_fmac_f32_e32 v192, v172, v180
	v_fmac_f32_e32 v193, v173, v180
	v_fmac_f32_e32 v194, v174, v180
	v_fmac_f32_e32 v195, v175, v180
	v_fmac_f32_e32 v196, v176, v180
	v_fmac_f32_e32 v197, v177, v180
	v_fmac_f32_e32 v198, v178, v180
	v_fmac_f32_e32 v199, v179, v180
	s_waitcnt vmcnt(31)
	v_sub_f32_e32 v182, v166, v167
	v_mul_f32_e32 v182, 0x3fb8aa3b, v182
	v_exp_f32_e32 v180, v182
	v_cvt_pk_bf16_f32 v188, v192, v193
	v_cvt_pk_bf16_f32 v189, v194, v195
	v_cvt_pk_bf16_f32 v190, v196, v197
	v_cvt_pk_bf16_f32 v191, v198, v199
	v_lshlrev_b32_e32 v172, 16, v120
	v_and_b32_e32 v173, 0xffff0000, v120
	v_lshlrev_b32_e32 v174, 16, v121
	v_and_b32_e32 v175, 0xffff0000, v121
	v_lshlrev_b32_e32 v176, 16, v122
	v_and_b32_e32 v177, 0xffff0000, v122
	v_lshlrev_b32_e32 v178, 16, v123
	v_and_b32_e32 v179, 0xffff0000, v123
	global_store_dwordx4 v2, v[188:191], s[20:21]
	s_add_u32 s20, s20, 0x20000
	s_addc_u32 s21, s21, 0
	v_fmac_f32_e32 v172, v192, v180
	v_fmac_f32_e32 v173, v193, v180
	v_fmac_f32_e32 v174, v194, v180
	v_fmac_f32_e32 v175, v195, v180
	v_fmac_f32_e32 v176, v196, v180
	v_fmac_f32_e32 v177, v197, v180
	v_fmac_f32_e32 v178, v198, v180
	v_fmac_f32_e32 v179, v199, v180
	s_waitcnt vmcnt(31)
	v_sub_f32_e32 v182, v167, v168
	v_mul_f32_e32 v182, 0x3fb8aa3b, v182
	v_exp_f32_e32 v180, v182
	v_cvt_pk_bf16_f32 v184, v172, v173
	v_cvt_pk_bf16_f32 v185, v174, v175
	v_cvt_pk_bf16_f32 v186, v176, v177
	v_cvt_pk_bf16_f32 v187, v178, v179
	v_lshlrev_b32_e32 v192, 16, v124
	v_and_b32_e32 v193, 0xffff0000, v124
	v_lshlrev_b32_e32 v194, 16, v125
	v_and_b32_e32 v195, 0xffff0000, v125
	v_lshlrev_b32_e32 v196, 16, v126
	v_and_b32_e32 v197, 0xffff0000, v126
	v_lshlrev_b32_e32 v198, 16, v127
	v_and_b32_e32 v199, 0xffff0000, v127
	global_store_dwordx4 v2, v[184:187], s[20:21]
	s_add_u32 s20, s20, 0x20000
	s_addc_u32 s21, s21, 0
	v_fmac_f32_e32 v192, v172, v180
	v_fmac_f32_e32 v193, v173, v180
	v_fmac_f32_e32 v194, v174, v180
	v_fmac_f32_e32 v195, v175, v180
	v_fmac_f32_e32 v196, v176, v180
	v_fmac_f32_e32 v197, v177, v180
	v_fmac_f32_e32 v198, v178, v180
	v_fmac_f32_e32 v199, v179, v180
	s_waitcnt vmcnt(31)
	v_sub_f32_e32 v182, v168, v169
	v_mul_f32_e32 v182, 0x3fb8aa3b, v182
	v_exp_f32_e32 v180, v182
	v_cvt_pk_bf16_f32 v188, v192, v193
	v_cvt_pk_bf16_f32 v189, v194, v195
	v_cvt_pk_bf16_f32 v190, v196, v197
	v_cvt_pk_bf16_f32 v191, v198, v199
	v_lshlrev_b32_e32 v172, 16, v128
	v_and_b32_e32 v173, 0xffff0000, v128
	v_lshlrev_b32_e32 v174, 16, v129
	v_and_b32_e32 v175, 0xffff0000, v129
	v_lshlrev_b32_e32 v176, 16, v130
	v_and_b32_e32 v177, 0xffff0000, v130
	v_lshlrev_b32_e32 v178, 16, v131
	v_and_b32_e32 v179, 0xffff0000, v131
	global_store_dwordx4 v2, v[188:191], s[20:21]
	s_add_u32 s20, s20, 0x20000
	s_addc_u32 s21, s21, 0
	v_fmac_f32_e32 v172, v192, v180
	v_fmac_f32_e32 v173, v193, v180
	v_fmac_f32_e32 v174, v194, v180
	v_fmac_f32_e32 v175, v195, v180
	v_fmac_f32_e32 v176, v196, v180
	v_fmac_f32_e32 v177, v197, v180
	v_fmac_f32_e32 v178, v198, v180
	v_fmac_f32_e32 v179, v199, v180
	s_waitcnt vmcnt(31)
	v_sub_f32_e32 v182, v169, v170
	v_mul_f32_e32 v182, 0x3fb8aa3b, v182
	v_exp_f32_e32 v180, v182
	v_cvt_pk_bf16_f32 v184, v172, v173
	v_cvt_pk_bf16_f32 v185, v174, v175
	v_cvt_pk_bf16_f32 v186, v176, v177
	v_cvt_pk_bf16_f32 v187, v178, v179
	v_lshlrev_b32_e32 v192, 16, v132
	v_and_b32_e32 v193, 0xffff0000, v132
	v_lshlrev_b32_e32 v194, 16, v133
	v_and_b32_e32 v195, 0xffff0000, v133
	v_lshlrev_b32_e32 v196, 16, v134
	v_and_b32_e32 v197, 0xffff0000, v134
	v_lshlrev_b32_e32 v198, 16, v135
	v_and_b32_e32 v199, 0xffff0000, v135
	global_store_dwordx4 v2, v[184:187], s[20:21]
	s_add_u32 s20, s20, 0x20000
	s_addc_u32 s21, s21, 0
	v_fmac_f32_e32 v192, v172, v180
	v_fmac_f32_e32 v193, v173, v180
	v_fmac_f32_e32 v194, v174, v180
	v_fmac_f32_e32 v195, v175, v180
	v_fmac_f32_e32 v196, v176, v180
	v_fmac_f32_e32 v197, v177, v180
	v_fmac_f32_e32 v198, v178, v180
	v_fmac_f32_e32 v199, v179, v180
	s_waitcnt vmcnt(31)
	v_sub_f32_e32 v182, v170, v171
	v_mul_f32_e32 v182, 0x3fb8aa3b, v182
	v_exp_f32_e32 v180, v182
	v_cvt_pk_bf16_f32 v188, v192, v193
	v_cvt_pk_bf16_f32 v189, v194, v195
	v_cvt_pk_bf16_f32 v190, v196, v197
	v_cvt_pk_bf16_f32 v191, v198, v199
	v_lshlrev_b32_e32 v172, 16, v136
	v_and_b32_e32 v173, 0xffff0000, v136
	v_lshlrev_b32_e32 v174, 16, v137
	v_and_b32_e32 v175, 0xffff0000, v137
	v_lshlrev_b32_e32 v176, 16, v138
	v_and_b32_e32 v177, 0xffff0000, v138
	v_lshlrev_b32_e32 v178, 16, v139
	v_and_b32_e32 v179, 0xffff0000, v139
	global_store_dwordx4 v2, v[188:191], s[20:21]
	v_fmac_f32_e32 v172, v192, v180
	v_fmac_f32_e32 v173, v193, v180
	v_fmac_f32_e32 v174, v194, v180
	v_fmac_f32_e32 v175, v195, v180
	v_fmac_f32_e32 v176, v196, v180
	v_fmac_f32_e32 v177, v197, v180
	v_fmac_f32_e32 v178, v198, v180
	v_fmac_f32_e32 v179, v199, v180
